# v101 plus MLA: the end-of-tile DMA wait and the two address multiplies also moved into the post-QK wait window
# baseline (speedup 1.0000x reference)
.Latt_mla_dmaend:
	s_waitcnt lgkmcnt(3)
	v_mfma_f32_32x32x16_bf16 v[64:79], v[112:115], v[130:133], v[96:111]
	ds_read_b128 v[112:115], v209 offset:160
	v_mfma_f32_32x32x16_bf16 v[64:79], v[116:119], v[134:137], v[64:79]
	ds_read_b128 v[116:119], v209 offset:192
	s_waitcnt lgkmcnt(3)
	v_mfma_f32_32x32x16_bf16 v[64:79], v[120:123], v[138:141], v[64:79]
	ds_read_b128 v[120:123], v209 offset:224
	v_mfma_f32_32x32x16_bf16 v[64:79], v[124:127], v[142:145], v[64:79]
	ds_read_b128 v[124:127], v209 offset:256
	s_waitcnt lgkmcnt(3)
	v_mfma_f32_32x32x16_bf16 v[64:79], v[250:253], v[146:149], v[64:79]
	ds_read_b128 v[250:253], v209 offset:288
	v_mfma_f32_32x32x16_bf16 v[64:79], v[112:115], v[150:153], v[64:79]
	ds_read_b128 v[112:115], v209 offset:320
	s_waitcnt lgkmcnt(3)
	v_mfma_f32_32x32x16_bf16 v[64:79], v[116:119], v[154:157], v[64:79]
	ds_read_b128 v[116:119], v209 offset:352
	v_mfma_f32_32x32x16_bf16 v[64:79], v[120:123], v[158:161], v[64:79]
	ds_read_b128 v[120:123], v209 offset:12800
	s_waitcnt lgkmcnt(3)
	v_mfma_f32_32x32x16_bf16 v[64:79], v[124:127], v[162:165], v[64:79]
	ds_read_b128 v[124:127], v209 offset:12832
	v_mfma_f32_32x32x16_bf16 v[64:79], v[250:253], v[166:169], v[64:79]
	ds_read_b128 v[250:253], v209 offset:12864
	s_waitcnt lgkmcnt(3)
	v_mfma_f32_32x32x16_bf16 v[64:79], v[112:115], v[170:173], v[64:79]
	ds_read_b128 v[112:115], v209 offset:12896
	v_mfma_f32_32x32x16_bf16 v[64:79], v[116:119], v[174:177], v[64:79]
	ds_read_b128 v[116:119], v209 offset:12928
	s_waitcnt lgkmcnt(3)
	v_mfma_f32_32x32x16_bf16 v[80:95], v[120:123], v[130:133], v[96:111]
	ds_read_b128 v[120:123], v209 offset:12960
	v_mfma_f32_32x32x16_bf16 v[80:95], v[124:127], v[134:137], v[80:95]
	ds_read_b128 v[124:127], v209 offset:12992
	s_waitcnt lgkmcnt(3)
	v_mfma_f32_32x32x16_bf16 v[80:95], v[250:253], v[138:141], v[80:95]
	ds_read_b128 v[250:253], v209 offset:13024
	v_mfma_f32_32x32x16_bf16 v[80:95], v[112:115], v[142:145], v[80:95]
	ds_read_b128 v[112:115], v209 offset:13056
	s_waitcnt lgkmcnt(3)
	v_mfma_f32_32x32x16_bf16 v[80:95], v[116:119], v[146:149], v[80:95]
	ds_read_b128 v[116:119], v209 offset:13088
	v_max3_f32 v211, v64, v65, v66
	v_mfma_f32_32x32x16_bf16 v[80:95], v[120:123], v[150:153], v[80:95]
	ds_read_b128 v[120:123], v209 offset:13120
	v_max3_f32 v213, v67, v68, v69
	s_waitcnt lgkmcnt(3)
	v_mfma_f32_32x32x16_bf16 v[80:95], v[124:127], v[154:157], v[80:95]
	ds_read_b128 v[124:127], v209 offset:13152
	v_max3_f32 v211, v211, v70, v71
	v_mfma_f32_32x32x16_bf16 v[80:95], v[250:253], v[158:161], v[80:95]
	v_max3_f32 v213, v213, v72, v73
	s_waitcnt lgkmcnt(2)
	v_mfma_f32_32x32x16_bf16 v[80:95], v[112:115], v[162:165], v[80:95]
	v_max3_f32 v211, v211, v74, v75
	v_mfma_f32_32x32x16_bf16 v[80:95], v[116:119], v[166:169], v[80:95]
	v_max3_f32 v213, v213, v76, v77
	s_waitcnt lgkmcnt(0)
	v_mfma_f32_32x32x16_bf16 v[80:95], v[120:123], v[170:173], v[80:95]
	v_max3_f32 v211, v211, v78, v79
	v_mfma_f32_32x32x16_bf16 v[80:95], v[124:127], v[174:177], v[80:95]
	ds_read_b128 v[112:115], v219 offset:0
	ds_read_b128 v[116:119], v219 offset:4608
	ds_read_b128 v[120:123], v219 offset:9216
	s_add_i32 s30, s52, 1
	s_cmp_lg_u32 s52, 2
	s_cselect_b32 s57, s30, 0
	s_add_i32 s49, s49, 64
	s_add_i32 s51, s51, 64
	s_mov_b32 s56, s53
	s_mov_b32 s53, s52
	s_mov_b32 s52, s57
	s_mul_i32 s57, s56, 0x6400
	s_mul_i32 s62, s56, 0x4800
	s_and_b64 vcc, exec, s[60:61]
	s_cbranch_vccnz .Latt_mla_w0
	s_waitcnt vmcnt(5)
.Latt_mla_wd:
	v_max3_f32 v215, v80, v81, v82
	v_max3_f32 v209, v83, v84, v85
	v_max3_f32 v215, v215, v86, v87
	v_max3_f32 v209, v209, v88, v89
	v_max3_f32 v215, v215, v90, v91
	v_max3_f32 v209, v209, v92, v93
	v_max3_f32 v215, v215, v94, v95
	v_max3_f32 v209, v209, v211, v213
	v_max_f32_e32 v209, v209, v215
	v_cmp_lt_f32_e32 vcc, s58, v209
	s_cbranch_vccnz .Latt_mla_rare

.Latt_mla_skip:
	s_add_i32 s55, s55, 1
	v_add_u32_e32 v209, s57, v246
	v_add_u32_e32 v219, s62, v247
	s_cmp_eq_u32 s20, s55
	s_barrier
	s_cbranch_scc0 .LBB0_178
	s_branch .LBB0_153
